# sc1 (write-through) on the gate/up epilogue stores of h so they do not linger in the XCD L2
# speedup vs baseline: 1.0015x; 1.0015x over previous
.LBB0_44:
	s_lshl_b32 s15, s64, 10
	s_and_b32 s15, s15, 0x1c00
	v_add_u32_e32 v147, s15, v143
	ds_read2_b32 v[154:155], v147 offset1:16
	ds_read2_b32 v[156:157], v147 offset0:32 offset1:48
	ds_read2_b32 v[158:159], v147 offset0:128 offset1:144
	s_nop 0
	v_pk_mul_f32 v[122:123], v[118:119], v[122:123]
	v_pk_mul_f32 v[130:131], v[126:127], v[130:131]
	v_lshl_add_u32 v146, s64, 8, v3
	v_lshl_or_b32 v140, s65, 7, v144
	s_nop 0
	s_waitcnt lgkmcnt(2)
	v_mul_f32_e32 v152, 0xbfb8aa3b, v154
	v_mul_f32_e32 v150, v124, v152
	v_mul_f32_e32 v151, v125, v152
	v_exp_f32_e32 v150, v150
	v_exp_f32_e32 v151, v151
	v_mul_f32_e32 v154, v154, v154
	v_pk_mul_f32 v[124:125], v[124:125], v[128:129]
	v_add_f32_e32 v150, 1.0, v150
	v_add_f32_e32 v151, 1.0, v151
	v_rcp_f32_e32 v150, v150
	v_rcp_f32_e32 v151, v151
	v_mul_f32_e32 v118, v118, v152
	v_mul_f32_e32 v119, v119, v152
	v_exp_f32_e32 v118, v118
	v_pk_mul_f32 v[128:129], v[154:155], v[150:151] op_sel_hi:[0,1]
	v_pk_mul_f32 v[124:125], v[124:125], v[128:129]
	v_mul_f32_e32 v128, v116, v152
	v_mul_f32_e32 v129, v117, v152
	v_exp_f32_e32 v128, v128
	v_exp_f32_e32 v129, v129
	v_exp_f32_e32 v119, v119
	v_mul_f32_e32 v126, v126, v152
	v_mul_f32_e32 v127, v127, v152
	v_exp_f32_e32 v126, v126
	v_exp_f32_e32 v127, v127
	v_add_f32_e32 v128, 1.0, v128
	v_add_f32_e32 v129, 1.0, v129
	v_rcp_f32_e32 v128, v128
	v_rcp_f32_e32 v129, v129
	v_add_f32_e32 v118, 1.0, v118
	v_add_f32_e32 v119, 1.0, v119
	v_rcp_f32_e32 v118, v118
	v_rcp_f32_e32 v119, v119
	v_add_f32_e32 v126, 1.0, v126
	v_add_f32_e32 v127, 1.0, v127
	v_rcp_f32_e32 v126, v126
	v_rcp_f32_e32 v127, v127
	v_pk_mul_f32 v[116:117], v[116:117], v[120:121]
	v_pk_mul_f32 v[120:121], v[154:155], v[128:129] op_sel_hi:[0,1]
	v_pk_mul_f32 v[116:117], v[116:117], v[120:121]
	v_pk_mul_f32 v[118:119], v[154:155], v[118:119] op_sel_hi:[0,1]
	v_pk_mul_f32 v[118:119], v[122:123], v[118:119]
	v_cvt_pk_bf16_f32 v122, v116, v117
	v_mov_b64_e32 v[116:117], s[4:5]
	s_ashr_i32 s15, s64, 3
	v_ashrrev_i32_e32 v141, 31, v140
	v_pk_mul_f32 v[126:127], v[154:155], v[126:127] op_sel_hi:[0,1]
	v_cvt_pk_bf16_f32 v123, v118, v119
	v_mad_i64_i32 v[118:119], s[36:37], v146, s35, v[116:117]
	v_pk_mul_f32 v[126:127], v[130:131], v[126:127]
	v_cvt_pk_bf16_f32 v120, v124, v125
	v_mad_i64_i32 v[124:125], s[36:37], s15, v215, v[118:119]
	v_lshlrev_b64 v[118:119], 1, v[140:141]
	v_cvt_pk_bf16_f32 v121, v126, v127
	v_lshl_add_u64 v[124:125], v[124:125], 0, v[118:119]
	global_store_dwordx4 v[124:125], v[120:123], off sc1
	v_pk_mul_f32 v[114:115], v[110:111], v[114:115]
	v_pk_mul_f32 v[106:107], v[102:103], v[106:107]
	v_mul_f32_e32 v121, 0xbfb8aa3b, v155
	v_mul_f32_e32 v122, v108, v121
	v_mul_f32_e32 v123, v109, v121
	v_exp_f32_e32 v122, v122
	v_exp_f32_e32 v123, v123
	v_mul_f32_e32 v120, v155, v155
	v_pk_mul_f32 v[108:109], v[108:109], v[112:113]
	v_add_f32_e32 v122, 1.0, v122
	v_add_f32_e32 v123, 1.0, v123
	v_rcp_f32_e32 v122, v122
	v_rcp_f32_e32 v123, v123
	v_mul_f32_e32 v110, v110, v121
	v_mul_f32_e32 v111, v111, v121
	v_exp_f32_e32 v110, v110
	v_pk_mul_f32 v[112:113], v[120:121], v[122:123] op_sel_hi:[0,1]
	v_pk_mul_f32 v[108:109], v[108:109], v[112:113]
	v_mul_f32_e32 v112, v100, v121
	v_mul_f32_e32 v113, v101, v121
	v_exp_f32_e32 v112, v112
	v_exp_f32_e32 v113, v113
	v_pk_mul_f32 v[100:101], v[100:101], v[104:105]
	v_exp_f32_e32 v111, v111
	v_add_f32_e32 v112, 1.0, v112
	v_add_f32_e32 v113, 1.0, v113
	v_rcp_f32_e32 v112, v112
	v_rcp_f32_e32 v113, v113
	v_add_f32_e32 v110, 1.0, v110
	v_add_f32_e32 v111, 1.0, v111
	v_rcp_f32_e32 v110, v110
	v_pk_mul_f32 v[104:105], v[120:121], v[112:113] op_sel_hi:[0,1]
	v_pk_mul_f32 v[104:105], v[100:101], v[104:105]
	v_mul_f32_e32 v100, v102, v121
	v_mul_f32_e32 v101, v103, v121
	v_exp_f32_e32 v100, v100
	v_exp_f32_e32 v101, v101
	v_rcp_f32_e32 v111, v111
	v_or_b32_e32 v112, 16, v146
	v_add_f32_e32 v100, 1.0, v100
	v_add_f32_e32 v101, 1.0, v101
	v_rcp_f32_e32 v100, v100
	v_rcp_f32_e32 v101, v101
	v_pk_mul_f32 v[110:111], v[120:121], v[110:111] op_sel_hi:[0,1]
	v_cvt_pk_bf16_f32 v102, v104, v105
	v_mad_i64_i32 v[104:105], s[36:37], v112, s35, v[116:117]
	v_pk_mul_f32 v[100:101], v[120:121], v[100:101] op_sel_hi:[0,1]
	v_pk_mul_f32 v[110:111], v[114:115], v[110:111]
	v_pk_mul_f32 v[106:107], v[106:107], v[100:101]
	v_mad_i64_i32 v[104:105], s[36:37], s15, v215, v[104:105]
	v_cvt_pk_bf16_f32 v100, v108, v109
	v_cvt_pk_bf16_f32 v101, v110, v111
	v_cvt_pk_bf16_f32 v103, v106, v107
	v_lshl_add_u64 v[104:105], v[104:105], 0, v[118:119]
	global_store_dwordx4 v[104:105], v[100:103], off sc1
	s_nop 0
	v_pk_mul_f32 v[98:99], v[94:95], v[98:99]
	v_pk_mul_f32 v[90:91], v[86:87], v[90:91]
	v_pk_mul_f32 v[82:83], v[78:79], v[82:83]
	v_pk_mul_f32 v[74:75], v[70:71], v[74:75]
	s_nop 0
	s_waitcnt lgkmcnt(1)
	v_mul_f32_e32 v104, 0xbfb8aa3b, v156
	v_mul_f32_e32 v102, v92, v104
	v_mul_f32_e32 v103, v93, v104
	v_exp_f32_e32 v102, v102
	v_exp_f32_e32 v103, v103
	v_mul_f32_e32 v156, v156, v156
	v_pk_mul_f32 v[92:93], v[92:93], v[96:97]
	v_add_f32_e32 v102, 1.0, v102
	v_add_f32_e32 v103, 1.0, v103
	v_rcp_f32_e32 v102, v102
	v_rcp_f32_e32 v103, v103
	v_mul_f32_e32 v94, v94, v104
	v_mul_f32_e32 v95, v95, v104
	v_exp_f32_e32 v94, v94
	v_pk_mul_f32 v[96:97], v[156:157], v[102:103] op_sel_hi:[0,1]
	v_pk_mul_f32 v[92:93], v[92:93], v[96:97]
	v_mul_f32_e32 v96, v84, v104
	v_mul_f32_e32 v97, v85, v104
	v_exp_f32_e32 v96, v96
	v_exp_f32_e32 v97, v97
	v_pk_mul_f32 v[84:85], v[84:85], v[88:89]
	v_exp_f32_e32 v95, v95
	v_add_f32_e32 v96, 1.0, v96
	v_add_f32_e32 v97, 1.0, v97
	v_rcp_f32_e32 v96, v96
	v_rcp_f32_e32 v97, v97
	v_add_f32_e32 v94, 1.0, v94
	v_add_f32_e32 v95, 1.0, v95
	v_rcp_f32_e32 v94, v94
	v_pk_mul_f32 v[88:89], v[156:157], v[96:97] op_sel_hi:[0,1]
	v_pk_mul_f32 v[88:89], v[84:85], v[88:89]
	v_mul_f32_e32 v84, v86, v104
	v_mul_f32_e32 v85, v87, v104
	v_exp_f32_e32 v84, v84
	v_exp_f32_e32 v85, v85
	v_rcp_f32_e32 v95, v95
	v_or_b32_e32 v96, 32, v146
	v_add_f32_e32 v84, 1.0, v84
	v_add_f32_e32 v85, 1.0, v85
	v_rcp_f32_e32 v84, v84
	v_rcp_f32_e32 v85, v85
	v_pk_mul_f32 v[94:95], v[156:157], v[94:95] op_sel_hi:[0,1]
	v_cvt_pk_bf16_f32 v86, v88, v89
	v_mad_i64_i32 v[88:89], s[36:37], v96, s35, v[116:117]
	v_pk_mul_f32 v[84:85], v[156:157], v[84:85] op_sel_hi:[0,1]
	v_pk_mul_f32 v[94:95], v[98:99], v[94:95]
	v_pk_mul_f32 v[90:91], v[90:91], v[84:85]
	v_mad_i64_i32 v[88:89], s[36:37], s15, v215, v[88:89]
	v_cvt_pk_bf16_f32 v84, v92, v93
	v_cvt_pk_bf16_f32 v85, v94, v95
	v_cvt_pk_bf16_f32 v87, v90, v91
	v_lshl_add_u64 v[88:89], v[88:89], 0, v[118:119]
	global_store_dwordx4 v[88:89], v[84:87], off sc1
	v_pk_mul_f32 v[66:67], v[62:63], v[66:67]
	v_pk_mul_f32 v[58:59], v[54:55], v[58:59]
	v_mul_f32_e32 v85, 0xbfb8aa3b, v157
	v_mul_f32_e32 v86, v76, v85
	v_mul_f32_e32 v87, v77, v85
	v_exp_f32_e32 v86, v86
	v_exp_f32_e32 v87, v87
	v_mul_f32_e32 v84, v157, v157
	v_pk_mul_f32 v[76:77], v[76:77], v[80:81]
	v_add_f32_e32 v86, 1.0, v86
	v_add_f32_e32 v87, 1.0, v87
	v_rcp_f32_e32 v86, v86
	v_rcp_f32_e32 v87, v87
	v_mul_f32_e32 v78, v78, v85
	v_mul_f32_e32 v79, v79, v85
	v_exp_f32_e32 v78, v78
	v_pk_mul_f32 v[80:81], v[84:85], v[86:87] op_sel_hi:[0,1]
	v_pk_mul_f32 v[76:77], v[76:77], v[80:81]
	v_mul_f32_e32 v80, v68, v85
	v_mul_f32_e32 v81, v69, v85
	v_exp_f32_e32 v80, v80
	v_exp_f32_e32 v81, v81
	v_pk_mul_f32 v[68:69], v[68:69], v[72:73]
	v_exp_f32_e32 v79, v79
	v_add_f32_e32 v80, 1.0, v80
	v_add_f32_e32 v81, 1.0, v81
	v_rcp_f32_e32 v80, v80
	v_rcp_f32_e32 v81, v81
	v_add_f32_e32 v78, 1.0, v78
	v_add_f32_e32 v79, 1.0, v79
	v_rcp_f32_e32 v78, v78
	v_pk_mul_f32 v[72:73], v[84:85], v[80:81] op_sel_hi:[0,1]
	v_pk_mul_f32 v[72:73], v[68:69], v[72:73]
	v_mul_f32_e32 v68, v70, v85
	v_mul_f32_e32 v69, v71, v85
	v_exp_f32_e32 v68, v68
	v_exp_f32_e32 v69, v69
	v_rcp_f32_e32 v79, v79
	v_or_b32_e32 v80, 48, v146
	v_add_f32_e32 v68, 1.0, v68
	v_add_f32_e32 v69, 1.0, v69
	v_rcp_f32_e32 v68, v68
	v_rcp_f32_e32 v69, v69
	v_pk_mul_f32 v[78:79], v[84:85], v[78:79] op_sel_hi:[0,1]
	v_cvt_pk_bf16_f32 v70, v72, v73
	v_mad_i64_i32 v[72:73], s[36:37], v80, s35, v[116:117]
	v_pk_mul_f32 v[68:69], v[84:85], v[68:69] op_sel_hi:[0,1]
	v_pk_mul_f32 v[78:79], v[82:83], v[78:79]
	v_pk_mul_f32 v[74:75], v[74:75], v[68:69]
	v_mad_i64_i32 v[72:73], s[36:37], s15, v215, v[72:73]
	v_cvt_pk_bf16_f32 v68, v76, v77
	v_cvt_pk_bf16_f32 v69, v78, v79
	v_cvt_pk_bf16_f32 v71, v74, v75
	v_lshl_add_u64 v[72:73], v[72:73], 0, v[118:119]
	global_store_dwordx4 v[72:73], v[68:71], off sc1
	s_nop 0
	v_add_u32_e32 v72, 0x80, v146
	v_pk_mul_f32 v[50:51], v[46:47], v[50:51]
	v_pk_mul_f32 v[42:43], v[38:39], v[42:43]
	v_pk_mul_f32 v[34:35], v[30:31], v[34:35]
	s_nop 0
	s_waitcnt lgkmcnt(0)
	v_mul_f32_e32 v73, 0xbfb8aa3b, v158
	v_mul_f32_e32 v70, v60, v73
	v_mul_f32_e32 v71, v61, v73
	v_exp_f32_e32 v70, v70
	v_exp_f32_e32 v71, v71
	v_mul_f32_e32 v158, v158, v158
	v_pk_mul_f32 v[60:61], v[60:61], v[64:65]
	v_add_f32_e32 v70, 1.0, v70
	v_add_f32_e32 v71, 1.0, v71
	v_rcp_f32_e32 v70, v70
	v_rcp_f32_e32 v71, v71
	v_mul_f32_e32 v62, v62, v73
	v_mul_f32_e32 v63, v63, v73
	v_exp_f32_e32 v62, v62
	v_pk_mul_f32 v[64:65], v[158:159], v[70:71] op_sel_hi:[0,1]
	v_pk_mul_f32 v[60:61], v[60:61], v[64:65]
	v_mul_f32_e32 v64, v52, v73
	v_mul_f32_e32 v65, v53, v73
	v_exp_f32_e32 v64, v64
	v_exp_f32_e32 v65, v65
	v_pk_mul_f32 v[52:53], v[52:53], v[56:57]
	v_exp_f32_e32 v63, v63
	v_add_f32_e32 v64, 1.0, v64
	v_add_f32_e32 v65, 1.0, v65
	v_rcp_f32_e32 v64, v64
	v_rcp_f32_e32 v65, v65
	v_add_f32_e32 v62, 1.0, v62
	v_add_f32_e32 v63, 1.0, v63
	v_rcp_f32_e32 v62, v62
	v_pk_mul_f32 v[56:57], v[158:159], v[64:65] op_sel_hi:[0,1]
	v_pk_mul_f32 v[56:57], v[52:53], v[56:57]
	v_mul_f32_e32 v52, v54, v73
	v_mul_f32_e32 v53, v55, v73
	v_exp_f32_e32 v52, v52
	v_exp_f32_e32 v53, v53
	v_rcp_f32_e32 v63, v63
	v_cvt_pk_bf16_f32 v54, v56, v57
	v_add_f32_e32 v52, 1.0, v52
	v_add_f32_e32 v53, 1.0, v53
	v_rcp_f32_e32 v52, v52
	v_rcp_f32_e32 v53, v53
	v_pk_mul_f32 v[62:63], v[158:159], v[62:63] op_sel_hi:[0,1]
	v_mad_i64_i32 v[56:57], s[36:37], v72, s35, v[116:117]
	v_pk_mul_f32 v[52:53], v[158:159], v[52:53] op_sel_hi:[0,1]
	v_pk_mul_f32 v[62:63], v[66:67], v[62:63]
	v_pk_mul_f32 v[58:59], v[58:59], v[52:53]
	v_mad_i64_i32 v[56:57], s[36:37], s15, v215, v[56:57]
	v_cvt_pk_bf16_f32 v52, v60, v61
	v_cvt_pk_bf16_f32 v53, v62, v63
	v_cvt_pk_bf16_f32 v55, v58, v59
	v_lshl_add_u64 v[56:57], v[56:57], 0, v[118:119]
	global_store_dwordx4 v[56:57], v[52:55], off sc1
	v_pk_mul_f32 v[26:27], v[22:23], v[26:27]
	v_pk_mul_f32 v[4:5], v[8:9], v[4:5]
	v_mul_f32_e32 v53, 0xbfb8aa3b, v159
	v_mul_f32_e32 v54, v44, v53
	v_mul_f32_e32 v55, v45, v53
	v_exp_f32_e32 v54, v54
	v_exp_f32_e32 v55, v55
	v_mul_f32_e32 v52, v159, v159
	v_pk_mul_f32 v[44:45], v[44:45], v[48:49]
	v_add_f32_e32 v54, 1.0, v54
	v_add_f32_e32 v55, 1.0, v55
	v_rcp_f32_e32 v54, v54
	v_rcp_f32_e32 v55, v55
	v_mul_f32_e32 v46, v46, v53
	v_mul_f32_e32 v47, v47, v53
	v_exp_f32_e32 v46, v46
	v_pk_mul_f32 v[48:49], v[52:53], v[54:55] op_sel_hi:[0,1]
	v_pk_mul_f32 v[44:45], v[44:45], v[48:49]
	v_mul_f32_e32 v48, v36, v53
	v_mul_f32_e32 v49, v37, v53
	v_exp_f32_e32 v48, v48
	v_exp_f32_e32 v49, v49
	v_pk_mul_f32 v[36:37], v[36:37], v[40:41]
	v_exp_f32_e32 v47, v47
	v_add_f32_e32 v48, 1.0, v48
	v_add_f32_e32 v49, 1.0, v49
	v_rcp_f32_e32 v48, v48
	v_rcp_f32_e32 v49, v49
	v_add_f32_e32 v46, 1.0, v46
	v_add_f32_e32 v47, 1.0, v47
	v_rcp_f32_e32 v46, v46
	v_pk_mul_f32 v[40:41], v[52:53], v[48:49] op_sel_hi:[0,1]
	v_pk_mul_f32 v[40:41], v[36:37], v[40:41]
	v_mul_f32_e32 v36, v38, v53
	v_mul_f32_e32 v37, v39, v53
	v_exp_f32_e32 v36, v36
	v_exp_f32_e32 v37, v37
	v_rcp_f32_e32 v47, v47
	v_add_u32_e32 v48, 0x90, v146
	v_add_f32_e32 v36, 1.0, v36
	v_add_f32_e32 v37, 1.0, v37
	v_rcp_f32_e32 v36, v36
	v_rcp_f32_e32 v37, v37
	v_pk_mul_f32 v[46:47], v[52:53], v[46:47] op_sel_hi:[0,1]
	v_cvt_pk_bf16_f32 v38, v40, v41
	v_mad_i64_i32 v[40:41], s[36:37], v48, s35, v[116:117]
	v_pk_mul_f32 v[36:37], v[52:53], v[36:37] op_sel_hi:[0,1]
	v_pk_mul_f32 v[46:47], v[50:51], v[46:47]
	v_pk_mul_f32 v[42:43], v[42:43], v[36:37]
	v_mad_i64_i32 v[40:41], s[36:37], s15, v215, v[40:41]
	v_cvt_pk_bf16_f32 v36, v44, v45
	v_cvt_pk_bf16_f32 v37, v46, v47
	v_cvt_pk_bf16_f32 v39, v42, v43
	v_lshl_add_u64 v[40:41], v[40:41], 0, v[118:119]
	global_store_dwordx4 v[40:41], v[36:39], off sc1
	ds_read2_b32 v[36:37], v147 offset0:160 offset1:176
	v_pk_mul_f32 v[18:19], v[14:15], v[18:19]
	v_pk_mul_f32 v[6:7], v[10:11], v[6:7]
	s_waitcnt lgkmcnt(0)
	s_andn2_b64 vcc, exec, s[6:7]
	s_waitcnt lgkmcnt(0)
	v_mul_f32_e32 v40, 0xbfb8aa3b, v36
	v_mul_f32_e32 v38, v28, v40
	v_mul_f32_e32 v39, v29, v40
	v_exp_f32_e32 v38, v38
	v_exp_f32_e32 v39, v39
	v_mul_f32_e32 v36, v36, v36
	v_pk_mul_f32 v[28:29], v[28:29], v[32:33]
	v_add_f32_e32 v38, 1.0, v38
	v_add_f32_e32 v39, 1.0, v39
	v_rcp_f32_e32 v38, v38
	v_rcp_f32_e32 v39, v39
	v_mul_f32_e32 v30, v30, v40
	v_mul_f32_e32 v31, v31, v40
	v_exp_f32_e32 v30, v30
	v_pk_mul_f32 v[32:33], v[36:37], v[38:39] op_sel_hi:[0,1]
	v_pk_mul_f32 v[28:29], v[28:29], v[32:33]
	v_mul_f32_e32 v32, v20, v40
	v_mul_f32_e32 v33, v21, v40
	v_exp_f32_e32 v32, v32
	v_exp_f32_e32 v33, v33
	v_pk_mul_f32 v[20:21], v[20:21], v[24:25]
	v_exp_f32_e32 v31, v31
	v_add_f32_e32 v32, 1.0, v32
	v_add_f32_e32 v33, 1.0, v33
	v_rcp_f32_e32 v32, v32
	v_rcp_f32_e32 v33, v33
	v_add_f32_e32 v30, 1.0, v30
	v_add_f32_e32 v31, 1.0, v31
	v_rcp_f32_e32 v30, v30
	v_pk_mul_f32 v[24:25], v[36:37], v[32:33] op_sel_hi:[0,1]
	v_pk_mul_f32 v[24:25], v[20:21], v[24:25]
	v_mul_f32_e32 v20, v22, v40
	v_mul_f32_e32 v21, v23, v40
	v_exp_f32_e32 v20, v20
	v_exp_f32_e32 v21, v21
	v_rcp_f32_e32 v31, v31
	v_add_u32_e32 v32, 0xa0, v146
	v_add_f32_e32 v20, 1.0, v20
	v_add_f32_e32 v21, 1.0, v21
	v_rcp_f32_e32 v20, v20
	v_rcp_f32_e32 v21, v21
	v_pk_mul_f32 v[30:31], v[36:37], v[30:31] op_sel_hi:[0,1]
	v_cvt_pk_bf16_f32 v22, v24, v25
	v_mad_i64_i32 v[24:25], s[36:37], v32, s35, v[116:117]
	v_pk_mul_f32 v[20:21], v[36:37], v[20:21] op_sel_hi:[0,1]
	v_pk_mul_f32 v[30:31], v[34:35], v[30:31]
	v_pk_mul_f32 v[26:27], v[26:27], v[20:21]
	v_mad_i64_i32 v[24:25], s[36:37], s15, v215, v[24:25]
	v_cvt_pk_bf16_f32 v20, v28, v29
	v_cvt_pk_bf16_f32 v21, v30, v31
	v_cvt_pk_bf16_f32 v23, v26, v27
	v_lshl_add_u64 v[24:25], v[24:25], 0, v[118:119]
	global_store_dwordx4 v[24:25], v[20:23], off sc1
	s_nop 1
	v_mul_f32_e32 v21, 0xbfb8aa3b, v37
	v_mul_f32_e32 v22, v12, v21
	v_mul_f32_e32 v23, v13, v21
	v_exp_f32_e32 v22, v22
	v_exp_f32_e32 v23, v23
	v_mul_f32_e32 v20, v37, v37
	v_pk_mul_f32 v[12:13], v[12:13], v[16:17]
	v_add_f32_e32 v22, 1.0, v22
	v_add_f32_e32 v23, 1.0, v23
	v_rcp_f32_e32 v22, v22
	v_rcp_f32_e32 v23, v23
	v_mul_f32_e32 v14, v14, v21
	v_mul_f32_e32 v15, v15, v21
	v_exp_f32_e32 v14, v14
	v_pk_mul_f32 v[16:17], v[20:21], v[22:23] op_sel_hi:[0,1]
	v_pk_mul_f32 v[12:13], v[12:13], v[16:17]
	v_mul_f32_e32 v16, v8, v21
	v_mul_f32_e32 v17, v9, v21
	v_exp_f32_e32 v16, v16
	v_exp_f32_e32 v17, v17
	v_exp_f32_e32 v15, v15
	v_add_f32_e32 v14, 1.0, v14
	v_add_f32_e32 v16, 1.0, v16
	v_add_f32_e32 v17, 1.0, v17
	v_rcp_f32_e32 v16, v16
	v_rcp_f32_e32 v17, v17
	v_add_f32_e32 v15, 1.0, v15
	v_rcp_f32_e32 v14, v14
	v_rcp_f32_e32 v15, v15
	v_pk_mul_f32 v[8:9], v[20:21], v[16:17] op_sel_hi:[0,1]
	v_pk_mul_f32 v[8:9], v[4:5], v[8:9]
	v_mul_f32_e32 v4, v10, v21
	v_mul_f32_e32 v5, v11, v21
	v_exp_f32_e32 v4, v4
	v_exp_f32_e32 v5, v5
	v_add_u32_e32 v16, 0xb0, v146
	v_pk_mul_f32 v[14:15], v[20:21], v[14:15] op_sel_hi:[0,1]
	v_add_f32_e32 v4, 1.0, v4
	v_add_f32_e32 v5, 1.0, v5
	v_rcp_f32_e32 v4, v4
	v_rcp_f32_e32 v5, v5
	v_pk_mul_f32 v[14:15], v[18:19], v[14:15]
	v_pk_mul_f32 v[4:5], v[20:21], v[4:5] op_sel_hi:[0,1]
	v_pk_mul_f32 v[10:11], v[6:7], v[4:5]
	v_cvt_pk_bf16_f32 v6, v8, v9
	v_mad_i64_i32 v[8:9], s[36:37], v16, s35, v[116:117]
	v_mad_i64_i32 v[8:9], s[36:37], s15, v215, v[8:9]
	v_cvt_pk_bf16_f32 v4, v12, v13
	v_cvt_pk_bf16_f32 v5, v14, v15
	v_cvt_pk_bf16_f32 v7, v10, v11
	v_lshl_add_u64 v[8:9], v[8:9], 0, v[118:119]
	s_mov_b64 s[36:37], -1
	global_store_dwordx4 v[8:9], v[4:7], off sc1
	s_cbranch_vccnz .LBB0_37
	s_andn2_b64 vcc, exec, s[8:9]
	s_cbranch_vccnz .LBB0_36
	s_barrier
	s_branch .LBB0_36
